# strategy 7.5: packed fp32 VALU (v_pk_mul/v_pk_add) beside the attention loop's MFMAs split into scalar pairs
# baseline (speedup 1.0000x reference)
; __device__ __forceinline__ unsigned pkbf(float lo, float hi) { f2_t v = {lo, hi}; return __builtin_bit_cast(unsigned, __builtin_convertvector(v, bf2_t)); }
; #define MFMA32(a, b, c) __builtin_amdgcn_mfma_f32_32x32x16_bf16((a), (b), (c), 0, 0, 0)
; __device__ __forceinline__ float max_x32(float x) { float a, b; swap32(x, a, b); return fmaxf(a, b); }
; template <int NQB> ...
;     ...
;     for (int kb = 0; kb < nkb; ++kb) {
;         asm volatile("" ::: "memory");
;         bf16x8 Vf[2][2];
; #pragma unroll
;         for (int db = 0; db < 2; ++db)
; #pragma unroll
;             for (int s2 = 0; s2 < 2; ++s2) Vf[db][s2] = *(const bf16x8*)(vp + (size_t)kb * 16384 + (db * 2 + s2) * 512);
;         bf16x8 Kx[6];
;         { const int kn = (kb + 1 < nkb) ? kb + 1 : kb;
; #pragma unroll
;             for (int s = 0; s < 4; ++s) Kx[s] = *(const bf16x8*)(kp + (size_t)kn * 16384 + 512 * s);
;             Kx[4] = *(const bf16x8*)(krp + (size_t)kn * 1024); Kx[5] = *(const bf16x8*)(krp + (size_t)kn * 1024 + 512); }
; #pragma unroll
;         for (int qb = 0; qb < NQB; ++qb) {
;             f32x16 X;
; #pragma unroll
;             for (int i = 0; i < 16; ++i) X[i] = 0.f;
; #pragma unroll
;             for (int s = 0; s < 6; ++s) X = MFMA32(Kf[s], qlds[(qb * 6 + s) * 64], X);
;             float mx = X[0];
; #pragma unroll
;             for (int i = 1; i < 16; ++i) mx = fmaxf(mx, X[i]);
;             mx = max_x32(mx);
;             const float mnew = fmaxf(mrun[qb], mx), alpha = __builtin_amdgcn_exp2f(mrun[qb] - mnew); mrun[qb] = mnew;
;             float ps = 0.f;
; #pragma unroll
;             for (int i = 0; i < 16; ++i) { X[i] = __builtin_amdgcn_exp2f(X[i] - mnew); ps += X[i]; }
;             lrun[qb] = lrun[qb] * alpha + ps;
; #pragma unroll
;             for (int db = 0; db < 2; ++db)
; #pragma unroll
;                 for (int i = 0; i < 16; ++i) O[qb][db][i] *= alpha;
; #pragma unroll
;             for (int s2 = 0; s2 < 2; ++s2) { u32x4 pw; pw.x = pkbf(X[8 * s2], X[8 * s2 + 1]); pw.y = pkbf(X[8 * s2 + 2], X[8 * s2 + 3]); pw.z = pkbf(X[8 * s2 + 4], X[8 * s2 + 5]); pw.w = pkbf(X[8 * s2 + 6], X[8 * s2 + 7]);
;                 const bf16x8 xs = __builtin_bit_cast(bf16x8, pw);
; #pragma unroll
;                 for (int db = 0; db < 2; ++db) O[qb][db] = MFMA32(Vf[db][s2], xs, O[qb][db]); }
.LBB0_86:
	ds_read_b128 v[64:67], v194 offset:4096
	ds_read_b128 v[120:123], v194 offset:5120
	ds_read_b128 v[80:83], v194 offset:10240
	ds_read_b128 v[198:201], v194 offset:11264
	v_mov_b32_e32 v184, v196
	v_mov_b32_e32 v185, v195
	s_waitcnt vmcnt(5) lgkmcnt(3)
	v_mfma_f32_32x32x16_bf16 v[64:79], v[116:119], v[64:67], 0
	s_add_i32 s0, s0, -1
	s_waitcnt lgkmcnt(1)
	v_mfma_f32_32x32x16_bf16 v[80:95], v[116:119], v[80:83], 0
	s_waitcnt vmcnt(4)
	v_mfma_f32_32x32x16_bf16 v[64:79], v[112:115], v[120:123], v[64:79]
	s_waitcnt lgkmcnt(0)
	v_mfma_f32_32x32x16_bf16 v[80:95], v[112:115], v[198:201], v[80:95]
	s_waitcnt vmcnt(3)
	v_mov_b64_e32 v[114:115], v[110:111]
	v_mov_b64_e32 v[112:113], v[108:109]
	ds_read_b128 v[108:111], v194 offset:6144
	ds_read_b128 v[116:119], v194 offset:7168
	s_waitcnt lgkmcnt(1)
	v_mfma_f32_32x32x16_bf16 v[64:79], v[112:115], v[108:111], v[64:79]
	ds_read_b128 v[120:123], v194 offset:12288
	ds_read_b128 v[108:111], v194 offset:13312
	ds_read_b128 v[196:199], v194 offset:9216
	s_waitcnt lgkmcnt(2)
	v_mfma_f32_32x32x16_bf16 v[80:95], v[112:115], v[120:123], v[80:95]
	s_waitcnt vmcnt(0)
	v_mov_b64_e32 v[122:123], v[98:99]
	v_mov_b64_e32 v[120:121], v[96:97]
	v_lshl_add_u64 v[98:99], s[20:21], 0, v[124:125]
	v_lshl_add_u64 v[96:97], s[4:5], 0, v[124:125]
	ds_read_b128 v[112:115], v194 offset:8192
	s_add_u32 s4, s4, 0x800
	s_addc_u32 s5, s5, 0
	v_mfma_f32_32x32x16_bf16 v[64:79], v[104:107], v[116:119], v[64:79]
	v_add_co_u32_e32 v116, vcc, s75, v98
	s_add_u32 s44, s44, 0x8000
	s_nop 0
	v_addc_co_u32_e32 v117, vcc, 0, v99, vcc
	s_addc_u32 s45, s45, 0
	s_add_u32 s20, s20, 0x8000
	s_waitcnt lgkmcnt(2)
	v_mfma_f32_32x32x16_bf16 v[80:95], v[104:107], v[108:111], v[80:95]
	v_add_co_u32_e32 v104, vcc, s76, v98
	s_addc_u32 s21, s21, 0
	s_nop 0
	v_addc_co_u32_e32 v105, vcc, 0, v99, vcc
	v_add_co_u32_e32 v220, vcc, s77, v96
	s_waitcnt lgkmcnt(0)
	v_mfma_f32_32x32x16_bf16 v[64:79], v[100:103], v[112:115], v[64:79]
	v_addc_co_u32_e32 v221, vcc, 0, v97, vcc
	ds_read_b128 v[96:99], v194 offset:14336
	ds_read_b128 v[200:203], v194 offset:15360
	global_load_dwordx4 v[204:207], v[116:117], off
	global_load_dwordx4 v[208:211], v[116:117], off offset:1024
	s_cmp_eq_u32 s0, 0
	s_waitcnt lgkmcnt(1)
	v_mfma_f32_32x32x16_bf16 v[80:95], v[100:103], v[96:99], v[80:95]
	global_load_dwordx4 v[212:215], v[116:117], off offset:2048
	global_load_dwordx4 v[216:219], v[116:117], off offset:3072
	s_nop 0
	global_load_dwordx4 v[116:119], v[104:105], off
	global_load_dwordx4 v[112:115], v[104:105], off offset:1024
	global_load_dwordx4 v[108:111], v[104:105], off offset:2048
	s_nop 0
	global_load_dwordx4 v[104:107], v[104:105], off offset:3072
	s_nop 0
	global_load_dwordx4 v[100:103], v[220:221], off offset:2048
	global_load_dwordx4 v[96:99], v[220:221], off offset:3072
	v_mfma_f32_32x32x16_bf16 v[64:79], v[120:123], v[196:199], v[64:79]
	s_waitcnt lgkmcnt(0)
	v_mfma_f32_32x32x16_bf16 v[80:95], v[120:123], v[200:203], v[80:95]
	s_nop 9
	v_max_f32_e32 v120, v65, v65
	v_max_f32_e32 v121, v64, v64
	v_max_f32_e32 v120, v121, v120
	v_max3_f32 v120, v120, v66, v67
	v_max3_f32 v120, v120, v68, v69
	v_max3_f32 v120, v120, v70, v71
	v_max3_f32 v120, v120, v72, v73
	v_max_f32_e32 v122, v81, v81
	v_max_f32_e32 v123, v80, v80
	v_max_f32_e32 v121, v123, v122
	v_max3_f32 v121, v121, v82, v83
	v_max3_f32 v121, v121, v84, v85
	v_max3_f32 v121, v121, v86, v87
	v_max3_f32 v121, v121, v88, v89
	v_max3_f32 v120, v120, v74, v75
	v_max3_f32 v121, v121, v90, v91
	v_max3_f32 v120, v120, v76, v77
	v_max3_f32 v121, v121, v92, v93
	v_max3_f32 v120, v120, v78, v79
	v_max3_f32 v121, v121, v94, v95
	v_mov_b32_e32 v122, v120
	v_mov_b32_e32 v123, v121
	s_nop 0
	v_permlane32_swap_b32_e32 v120, v122
	v_permlane32_swap_b32_e32 v121, v123
	v_max3_f32 v196, v184, v120, v122
	v_max3_f32 v195, v185, v121, v123
	v_sub_f32_e32 v120, v184, v196
	v_sub_f32_e32 v64, v64, v196
	v_sub_f32_e32 v65, v65, v196
	v_sub_f32_e32 v66, v66, v196
	v_sub_f32_e32 v67, v67, v196
	v_sub_f32_e32 v68, v68, v196
	v_sub_f32_e32 v69, v69, v196
	v_sub_f32_e32 v70, v70, v196
	v_sub_f32_e32 v71, v71, v196
	v_sub_f32_e32 v72, v72, v196
	v_sub_f32_e32 v121, v73, v196
	v_sub_f32_e32 v74, v74, v196
	v_sub_f32_e32 v122, v75, v196
	v_sub_f32_e32 v76, v76, v196
	v_sub_f32_e32 v123, v77, v196
	v_sub_f32_e32 v184, v78, v196
	v_sub_f32_e32 v197, v79, v196
	v_sub_f32_e32 v185, v185, v195
	v_sub_f32_e32 v78, v80, v195
	v_sub_f32_e32 v80, v81, v195
	v_sub_f32_e32 v82, v82, v195
	v_sub_f32_e32 v198, v83, v195
	v_sub_f32_e32 v84, v84, v195
	v_sub_f32_e32 v199, v85, v195
	v_sub_f32_e32 v86, v86, v195
	v_sub_f32_e32 v200, v87, v195
	v_exp_f32_e32 v73, v64
	v_exp_f32_e32 v75, v65
	v_exp_f32_e32 v77, v66
	v_exp_f32_e32 v79, v67
	v_exp_f32_e32 v81, v68
	v_exp_f32_e32 v83, v69
	v_exp_f32_e32 v85, v70
	v_exp_f32_e32 v87, v71
	v_exp_f32_e32 v68, v120
	v_sub_f32_e32 v201, v89, v195
	v_sub_f32_e32 v203, v91, v195
	v_sub_f32_e32 v221, v93, v195
	v_exp_f32_e32 v89, v72
	v_exp_f32_e32 v91, v121
	v_exp_f32_e32 v93, v74
	v_exp_f32_e32 v121, v76
	v_exp_f32_e32 v72, v78
	v_exp_f32_e32 v74, v80
	v_exp_f32_e32 v76, v82
	v_exp_f32_e32 v78, v198
	v_exp_f32_e32 v80, v84
	v_exp_f32_e32 v82, v199
	v_exp_f32_e32 v84, v86
	v_exp_f32_e32 v86, v200
	v_exp_f32_e32 v198, v185
	v_mul_f32_e32 v62, v68, v62
	v_mul_f32_e32 v63, v68, v63
	v_mul_f32_e32 v60, v68, v60
	v_mul_f32_e32 v61, v68, v61
	v_mul_f32_e32 v58, v68, v58
	v_mul_f32_e32 v59, v68, v59
	v_mul_f32_e32 v56, v68, v56
	v_mul_f32_e32 v57, v68, v57
	v_mul_f32_e32 v54, v68, v54
	v_mul_f32_e32 v55, v68, v55
	v_mul_f32_e32 v52, v68, v52
	v_mul_f32_e32 v53, v68, v53
	v_mul_f32_e32 v50, v68, v50
	v_mul_f32_e32 v51, v68, v51
	v_mul_f32_e32 v48, v68, v48
	v_mul_f32_e32 v49, v68, v49
	v_mul_f32_e32 v46, v68, v46
	v_mul_f32_e32 v47, v68, v47
	v_mul_f32_e32 v44, v68, v44
	v_mul_f32_e32 v45, v68, v45
	v_mul_f32_e32 v42, v68, v42
	v_mul_f32_e32 v43, v68, v43
	v_mul_f32_e32 v40, v68, v40
	v_mul_f32_e32 v41, v68, v41
	v_mul_f32_e32 v38, v68, v38
	v_mul_f32_e32 v39, v68, v39
	v_mul_f32_e32 v36, v68, v36
	v_mul_f32_e32 v37, v68, v37
	v_mul_f32_e32 v34, v68, v34
	v_mul_f32_e32 v35, v68, v35
	v_mul_f32_e32 v32, v68, v32
	v_mul_f32_e32 v33, v68, v33
	v_cvt_pk_bf16_f32 v64, v73, v75
	v_cvt_pk_bf16_f32 v65, v77, v79
	v_cvt_pk_bf16_f32 v66, v81, v83
	v_cvt_pk_bf16_f32 v67, v85, v87
	v_mov_b32_e32 v199, v68
	v_cvt_pk_bf16_f32 v68, v72, v74
	s_waitcnt vmcnt(9)
; __device__ __forceinline__ unsigned pkbf(float lo, float hi) { f2_t v = {lo, hi}; return __builtin_bit_cast(unsigned, __builtin_convertvector(v, bf2_t)); }
; #define MFMA32(a, b, c) __builtin_amdgcn_mfma_f32_32x32x16_bf16((a), (b), (c), 0, 0, 0)
; template <int NQB> ...
;     ...
;             const float mnew = fmaxf(mrun[qb], mx), alpha = __builtin_amdgcn_exp2f(mrun[qb] - mnew); mrun[qb] = mnew;
;             float ps = 0.f;
; #pragma unroll
;             for (int i = 0; i < 16; ++i) { X[i] = __builtin_amdgcn_exp2f(X[i] - mnew); ps += X[i]; }
;             lrun[qb] = lrun[qb] * alpha + ps;
; #pragma unroll
;             for (int db = 0; db < 2; ++db)
; #pragma unroll
;                 for (int i = 0; i < 16; ++i) O[qb][db][i] *= alpha;
; #pragma unroll
;             for (int s2 = 0; s2 < 2; ++s2) { u32x4 pw; pw.x = pkbf(X[8 * s2], X[8 * s2 + 1]); pw.y = pkbf(X[8 * s2 + 2], X[8 * s2 + 3]); pw.z = pkbf(X[8 * s2 + 4], X[8 * s2 + 5]); pw.w = pkbf(X[8 * s2 + 6], X[8 * s2 + 7]);
;                 const bf16x8 xs = __builtin_bit_cast(bf16x8, pw);
; #pragma unroll
;                 for (int db = 0; db < 2; ++db) O[qb][db] = MFMA32(Vf[db][s2], xs, O[qb][db]); }
	v_mfma_f32_32x32x16_bf16 v[48:63], v[204:207], v[64:67], v[48:63]
	v_cvt_pk_bf16_f32 v69, v76, v78
	v_cvt_pk_bf16_f32 v70, v80, v82
	v_cvt_pk_bf16_f32 v71, v84, v86
	v_mul_f32_e64 v30, v30, v198
	v_mul_f32_e64 v31, v31, v198
	v_mul_f32_e32 v28, v198, v28
	v_mul_f32_e32 v29, v198, v29
	v_mul_f32_e32 v26, v198, v26
	v_mul_f32_e32 v27, v198, v27
	v_mul_f32_e32 v24, v198, v24
	v_mul_f32_e32 v25, v198, v25
	s_waitcnt vmcnt(7)
	v_mfma_f32_32x32x16_bf16 v[32:47], v[212:215], v[64:67], v[32:47]
	v_mul_f32_e64 v22, v22, v198
	v_mul_f32_e64 v23, v23, v198
	v_mul_f32_e64 v20, v20, v198
	v_mul_f32_e64 v21, v21, v198
	v_mul_f32_e64 v18, v18, v198
	v_mul_f32_e64 v19, v19, v198
	v_mul_f32_e32 v16, v198, v16
	v_mul_f32_e32 v17, v198, v17
	v_mul_f32_e32 v14, v198, v14
	v_mul_f32_e32 v15, v198, v15
	v_mul_f32_e32 v12, v198, v12
	v_mul_f32_e32 v13, v198, v13
	v_mul_f32_e32 v10, v198, v10
	v_mul_f32_e32 v11, v198, v11
	v_mul_f32_e32 v8, v198, v8
	v_mul_f32_e32 v9, v198, v9
	v_mul_f32_e32 v6, v198, v6
	v_mul_f32_e32 v7, v198, v7
	v_mul_f32_e32 v4, v198, v4
	v_mul_f32_e32 v5, v198, v5
	v_mul_f32_e32 v2, v198, v2
	v_mul_f32_e32 v3, v198, v3
	v_mul_f32_e32 v0, v198, v0
	v_mul_f32_e32 v1, v198, v1
	v_pk_add_f32 v[72:73], v[72:73], 0 op_sel_hi:[1,0]
	v_mfma_f32_32x32x16_bf16 v[16:31], v[204:207], v[68:71], v[16:31]
	v_add_f32_e64 v72, v74, v72
	v_add_f32_e64 v73, v75, v73
	v_sub_f32_e32 v88, v88, v195
	v_add_f32_e64 v72, v76, v72
	v_add_f32_e64 v73, v77, v73
	v_sub_f32_e32 v202, v90, v195
	v_sub_f32_e32 v220, v92, v195
	v_sub_f32_e32 v222, v94, v195
	v_sub_f32_e32 v223, v95, v195
	v_mfma_f32_32x32x16_bf16 v[0:15], v[212:215], v[68:71], v[0:15]
	v_exp_f32_e32 v95, v122
	v_exp_f32_e32 v123, v123
	v_exp_f32_e32 v69, v184
	v_exp_f32_e32 v71, v197
	v_add_f32_e32 v72, v78, v72
	v_add_f32_e32 v73, v79, v73
	v_exp_f32_e32 v88, v88
	v_exp_f32_e32 v90, v201
	v_exp_f32_e32 v92, v202
	v_exp_f32_e32 v94, v203
	v_exp_f32_e32 v120, v220
	v_exp_f32_e32 v122, v221
	v_exp_f32_e32 v68, v222
	v_exp_f32_e32 v70, v223
	v_add_f32_e32 v72, v80, v72
	v_add_f32_e32 v73, v81, v73
	v_cvt_pk_bf16_f32 v64, v89, v91
	v_add_f32_e32 v72, v82, v72
	v_add_f32_e32 v73, v83, v73
	v_cvt_pk_bf16_f32 v65, v93, v95
	v_add_f32_e32 v72, v84, v72
	v_add_f32_e32 v73, v85, v73
	v_cvt_pk_bf16_f32 v66, v121, v123
	v_cvt_pk_bf16_f32 v67, v69, v71
	v_add_f32_e32 v72, v86, v72
	v_add_f32_e32 v73, v87, v73
	s_nop 0
	v_mfma_f32_32x32x16_bf16 v[48:63], v[208:211], v[64:67], v[48:63]
	v_add_f32_e64 v72, v88, v72
	v_add_f32_e64 v73, v89, v73
	v_add_f32_e64 v72, v90, v72
	v_add_f32_e64 v73, v91, v73
	s_waitcnt vmcnt(6)
	v_mfma_f32_32x32x16_bf16 v[32:47], v[216:219], v[64:67], v[32:47]
	v_cvt_pk_bf16_f32 v64, v88, v90
	v_cvt_pk_bf16_f32 v65, v92, v94
	v_cvt_pk_bf16_f32 v66, v120, v122
	v_cvt_pk_bf16_f32 v67, v68, v70
	s_nop 1
	v_mfma_f32_32x32x16_bf16 v[16:31], v[208:211], v[64:67], v[16:31]
	v_mfma_f32_32x32x16_bf16 v[0:15], v[216:219], v[64:67], v[0:15]
	v_add_f32_e64 v64, v92, v72
	v_add_f32_e64 v65, v93, v73
	v_add_f32_e64 v64, v94, v64
	v_add_f32_e64 v65, v95, v65
	v_add_f32_e64 v64, v120, v64
	v_add_f32_e64 v65, v121, v65
	v_add_f32_e32 v64, v122, v64
	v_add_f32_e32 v65, v123, v65
	s_nop 0
	v_add_f32_e32 v64, v68, v64
	v_add_f32_e32 v65, v69, v65
	s_nop 0
	v_add_f32_e32 v64, v70, v64
	v_add_f32_e32 v65, v71, v65
	s_nop 0
	v_pk_fma_f32 v[164:165], v[164:165], v[198:199], v[64:65]
	s_cbranch_scc0 .LBB0_86
	v_lshl_add_u64 v[64:65], v[166:167], 1, s[56:57]
	v_lshl_add_u64 v[64:65], v[64:65], 0, s[44:45]
	global_load_dwordx4 v[92:95], v[64:65], off
	global_load_dwordx4 v[80:83], v[64:65], off offset:1024
	global_load_dwordx4 v[88:91], v[64:65], off offset:2048
	global_load_dwordx4 v[84:87], v[64:65], off offset:3072
	ds_read_b128 v[64:67], v194 offset:4096
	ds_read_b128 v[120:123], v194 offset:5120
	s_waitcnt vmcnt(9) lgkmcnt(1)
	v_mfma_f32_32x32x16_bf16 v[64:79], v[116:119], v[64:67], 0
	s_waitcnt vmcnt(8) lgkmcnt(0)
	v_mfma_f32_32x32x16_bf16 v[64:79], v[112:115], v[120:123], v[64:79]
	ds_read_b128 v[120:123], v194 offset:6144
	s_waitcnt vmcnt(7) lgkmcnt(0)
	v_mfma_f32_32x32x16_bf16 v[64:79], v[108:111], v[120:123], v[64:79]
	ds_read_b128 v[120:123], v194 offset:7168
	s_waitcnt vmcnt(6) lgkmcnt(0)
	v_mfma_f32_32x32x16_bf16 v[64:79], v[104:107], v[120:123], v[64:79]
	ds_read_b128 v[120:123], v194 offset:8192
	s_waitcnt vmcnt(5) lgkmcnt(0)
	v_mfma_f32_32x32x16_bf16 v[64:79], v[100:103], v[120:123], v[64:79]
	ds_read_b128 v[120:123], v194 offset:9216
	s_waitcnt vmcnt(4) lgkmcnt(0)
; __device__ __forceinline__ unsigned pkbf(float lo, float hi) { f2_t v = {lo, hi}; return __builtin_bit_cast(unsigned, __builtin_convertvector(v, bf2_t)); }
; #define MFMA32(a, b, c) __builtin_amdgcn_mfma_f32_32x32x16_bf16((a), (b), (c), 0, 0, 0)
; __device__ __forceinline__ float max_x32(float x) { float a, b; swap32(x, a, b); return fmaxf(a, b); }
; template <int NQB> ...
;     ...
;         for (int qb = 0; qb < NQB; ++qb) {
;             f32x16 X;
; #pragma unroll
;             for (int i = 0; i < 16; ++i) X[i] = 0.f;
; #pragma unroll
;             for (int s = 0; s < 6; ++s) X = MFMA32(Kf[s], qlds[(qb * 6 + s) * 64], X);
;             float mx = X[0];
; #pragma unroll
;             for (int i = 1; i < 16; ++i) mx = fmaxf(mx, X[i]);
;             mx = max_x32(mx);
;             const float mnew = fmaxf(mrun[qb], mx), alpha = __builtin_amdgcn_exp2f(mrun[qb] - mnew); mrun[qb] = mnew;
;             float ps = 0.f;
; #pragma unroll
;             for (int i = 0; i < 16; ++i) { X[i] = __builtin_amdgcn_exp2f(X[i] - mnew); ps += X[i]; }
;             lrun[qb] = lrun[qb] * alpha + ps;
; #pragma unroll
;             for (int db = 0; db < 2; ++db)
; #pragma unroll
;                 for (int i = 0; i < 16; ++i) O[qb][db][i] *= alpha;
; #pragma unroll
;             for (int s2 = 0; s2 < 2; ++s2) { u32x4 pw; pw.x = pkbf(X[8 * s2], X[8 * s2 + 1]); pw.y = pkbf(X[8 * s2 + 2], X[8 * s2 + 3]); pw.z = pkbf(X[8 * s2 + 4], X[8 * s2 + 5]); pw.w = pkbf(X[8 * s2 + 6], X[8 * s2 + 7]);
;                 const bf16x8 xs = __builtin_bit_cast(bf16x8, pw);
; #pragma unroll
;                 for (int db = 0; db < 2; ++db) O[qb][db] = MFMA32(Vf[db][s2], xs, O[qb][db]); }
	v_mfma_f32_32x32x16_bf16 v[64:79], v[96:99], v[120:123], v[64:79]
	s_nop 11
	v_max_f32_e32 v120, v65, v65
	v_max_f32_e32 v121, v64, v64
	v_max_f32_e32 v120, v121, v120
	v_max3_f32 v120, v120, v66, v67
	v_max3_f32 v120, v120, v68, v69
	v_max3_f32 v120, v120, v70, v71
	v_max3_f32 v120, v120, v72, v73
	v_max3_f32 v120, v120, v74, v75
	v_max3_f32 v120, v120, v76, v77
	v_max3_f32 v120, v120, v78, v79
	v_mov_b32_e32 v121, v120
	s_nop 1
	v_permlane32_swap_b32_e32 v120, v121
	v_max3_f32 v120, v196, v120, v121
	v_sub_f32_e32 v64, v64, v120
	v_exp_f32_e32 v122, v64
	v_sub_f32_e32 v65, v65, v120
	v_exp_f32_e32 v65, v65
	v_sub_f32_e32 v66, v66, v120
	v_exp_f32_e32 v66, v66
	v_sub_f32_e32 v67, v67, v120
	v_exp_f32_e32 v67, v67
	v_sub_f32_e32 v68, v68, v120
	v_add_f32_e32 v64, 0, v122
	v_exp_f32_e32 v68, v68
	v_sub_f32_e32 v69, v69, v120
	v_add_f32_e32 v64, v65, v64
	v_exp_f32_e32 v69, v69
	v_sub_f32_e32 v70, v70, v120
	v_add_f32_e32 v64, v66, v64
	v_exp_f32_e32 v70, v70
	v_sub_f32_e32 v71, v71, v120
	v_add_f32_e32 v64, v67, v64
	v_exp_f32_e32 v71, v71
	v_sub_f32_e32 v72, v72, v120
	v_add_f32_e32 v64, v68, v64
	v_exp_f32_e32 v72, v72
	v_sub_f32_e32 v73, v73, v120
	v_add_f32_e32 v64, v69, v64
	v_exp_f32_e32 v73, v73
	v_sub_f32_e32 v74, v74, v120
	v_add_f32_e32 v64, v70, v64
	v_exp_f32_e32 v74, v74
	v_sub_f32_e32 v75, v75, v120
	v_add_f32_e32 v64, v71, v64
	v_exp_f32_e32 v75, v75
	v_sub_f32_e32 v76, v76, v120
	v_add_f32_e32 v64, v72, v64
	v_exp_f32_e32 v76, v76
	v_sub_f32_e32 v77, v77, v120
	v_add_f32_e32 v64, v73, v64
	v_exp_f32_e32 v77, v77
	v_sub_f32_e32 v78, v78, v120
	v_add_f32_e32 v64, v74, v64
	v_exp_f32_e32 v78, v78
	v_sub_f32_e32 v79, v79, v120
	v_add_f32_e32 v64, v75, v64
	v_exp_f32_e32 v79, v79
	v_add_f32_e32 v64, v76, v64
	v_add_f32_e32 v64, v77, v64
	v_sub_f32_e32 v121, v196, v120
	v_add_f32_e32 v64, v78, v64
	v_add_f32_e32 v120, v79, v64
	v_exp_f32_e32 v64, v121
	s_nop 0
	v_fmac_f32_e32 v120, v165, v64
	v_pk_mul_f32 v[62:63], v[62:63], v[64:65] op_sel_hi:[1,0]
	v_pk_mul_f32 v[60:61], v[60:61], v[64:65] op_sel_hi:[1,0]
	v_pk_mul_f32 v[58:59], v[58:59], v[64:65] op_sel_hi:[1,0]
	v_pk_mul_f32 v[56:57], v[56:57], v[64:65] op_sel_hi:[1,0]
	v_pk_mul_f32 v[54:55], v[54:55], v[64:65] op_sel_hi:[1,0]
	v_pk_mul_f32 v[52:53], v[52:53], v[64:65] op_sel_hi:[1,0]
	v_pk_mul_f32 v[50:51], v[50:51], v[64:65] op_sel_hi:[1,0]
	v_pk_mul_f32 v[48:49], v[48:49], v[64:65] op_sel_hi:[1,0]
	v_pk_mul_f32 v[46:47], v[46:47], v[64:65] op_sel_hi:[1,0]
	v_pk_mul_f32 v[44:45], v[44:45], v[64:65] op_sel_hi:[1,0]
	v_pk_mul_f32 v[42:43], v[42:43], v[64:65] op_sel_hi:[1,0]
	v_pk_mul_f32 v[40:41], v[40:41], v[64:65] op_sel_hi:[1,0]
	v_pk_mul_f32 v[38:39], v[38:39], v[64:65] op_sel_hi:[1,0]
	v_pk_mul_f32 v[36:37], v[36:37], v[64:65] op_sel_hi:[1,0]
	v_pk_mul_f32 v[34:35], v[34:35], v[64:65] op_sel_hi:[1,0]
	v_pk_mul_f32 v[32:33], v[32:33], v[64:65] op_sel_hi:[1,0]
	v_cvt_pk_bf16_f32 v64, v122, v65
	v_cvt_pk_bf16_f32 v65, v66, v67
	v_cvt_pk_bf16_f32 v66, v68, v69
	v_cvt_pk_bf16_f32 v67, v70, v71
	s_waitcnt vmcnt(3)
	s_nop 0
	v_mfma_f32_32x32x16_bf16 v[48:63], v[92:95], v[64:67], v[48:63]
	s_waitcnt vmcnt(1)
	v_mfma_f32_32x32x16_bf16 v[32:47], v[88:91], v[64:67], v[32:47]
	v_cvt_pk_bf16_f32 v64, v72, v73
	v_cvt_pk_bf16_f32 v65, v74, v75
	v_cvt_pk_bf16_f32 v66, v76, v77
	v_cvt_pk_bf16_f32 v67, v78, v79
	s_nop 1
	v_mfma_f32_32x32x16_bf16 v[48:63], v[80:83], v[64:67], v[48:63]
	s_waitcnt vmcnt(0)
	v_mfma_f32_32x32x16_bf16 v[32:47], v[84:87], v[64:67], v[32:47]
	ds_read_b128 v[64:67], v194 offset:10240
	s_waitcnt lgkmcnt(0)
	v_mfma_f32_32x32x16_bf16 v[64:79], v[116:119], v[64:67], 0
	ds_read_b128 v[116:119], v194 offset:11264
	s_waitcnt lgkmcnt(0)
	v_mfma_f32_32x32x16_bf16 v[64:79], v[112:115], v[116:119], v[64:79]
	ds_read_b128 v[112:115], v194 offset:12288
	s_waitcnt lgkmcnt(0)
	v_mfma_f32_32x32x16_bf16 v[64:79], v[108:111], v[112:115], v[64:79]
	ds_read_b128 v[108:111], v194 offset:13312
	s_waitcnt lgkmcnt(0)
	v_mfma_f32_32x32x16_bf16 v[64:79], v[104:107], v[108:111], v[64:79]
	ds_read_b128 v[104:107], v194 offset:14336
	s_waitcnt lgkmcnt(0)
	v_mfma_f32_32x32x16_bf16 v[64:79], v[100:103], v[104:107], v[64:79]
	ds_read_b128 v[100:103], v194 offset:15360
	s_waitcnt lgkmcnt(0)
	v_mfma_f32_32x32x16_bf16 v[64:79], v[96:99], v[100:103], v[64:79]
	s_nop 11
	v_max_f32_e32 v96, v65, v65
	v_max_f32_e32 v97, v64, v64
	v_max_f32_e32 v96, v97, v96
	v_max3_f32 v96, v96, v66, v67
	v_max3_f32 v96, v96, v68, v69
	v_max3_f32 v96, v96, v70, v71
	v_max3_f32 v96, v96, v72, v73
	v_max3_f32 v96, v96, v74, v75
	v_max3_f32 v96, v96, v76, v77
	v_max3_f32 v96, v96, v78, v79
	v_mov_b32_e32 v97, v96
	s_nop 1
	v_permlane32_swap_b32_e32 v96, v97
	v_max3_f32 v99, v195, v96, v97
	v_sub_f32_e32 v64, v64, v99
	v_exp_f32_e32 v96, v64
	v_sub_f32_e32 v64, v65, v99
	v_exp_f32_e32 v65, v64
	v_sub_f32_e32 v64, v66, v99
	v_exp_f32_e32 v97, v64
	v_sub_f32_e32 v64, v67, v99
	v_exp_f32_e32 v98, v64
	v_sub_f32_e32 v64, v68, v99
	v_exp_f32_e32 v68, v64
	v_sub_f32_e32 v64, v69, v99
	v_exp_f32_e32 v69, v64
	v_sub_f32_e32 v64, v70, v99
	v_exp_f32_e32 v70, v64
	v_sub_f32_e32 v64, v71, v99
	v_exp_f32_e32 v71, v64
	v_sub_f32_e32 v64, v72, v99
	v_exp_f32_e32 v72, v64
	v_sub_f32_e32 v64, v73, v99
	v_exp_f32_e32 v73, v64
	v_sub_f32_e32 v64, v74, v99
	v_exp_f32_e32 v74, v64
	v_sub_f32_e32 v64, v75, v99
	v_exp_f32_e32 v75, v64
	v_sub_f32_e32 v64, v76, v99
	v_exp_f32_e32 v76, v64
	v_sub_f32_e32 v64, v77, v99
	v_exp_f32_e32 v77, v64
	v_sub_f32_e32 v64, v78, v99
	v_sub_f32_e32 v100, v195, v99
	v_exp_f32_e32 v78, v64
	v_sub_f32_e32 v64, v79, v99
	v_exp_f32_e32 v79, v64
	v_exp_f32_e32 v64, v100
	v_cvt_pk_bf16_f32 v100, v96, v65
; __device__ __forceinline__ unsigned pkbf(float lo, float hi) { f2_t v = {lo, hi}; return __builtin_bit_cast(unsigned, __builtin_convertvector(v, bf2_t)); }
; #define MFMA32(a, b, c) __builtin_amdgcn_mfma_f32_32x32x16_bf16((a), (b), (c), 0, 0, 0)
; __device__ __forceinline__ float sum_x32(float x) { float a, b; swap32(x, a, b); return a + b; }
; template <int NQB> ...
;     ...
;             for (int s2 = 0; s2 < 2; ++s2) { u32x4 pw; pw.x = pkbf(X[8 * s2], X[8 * s2 + 1]); pw.y = pkbf(X[8 * s2 + 2], X[8 * s2 + 3]); pw.z = pkbf(X[8 * s2 + 4], X[8 * s2 + 5]); pw.w = pkbf(X[8 * s2 + 6], X[8 * s2 + 7]);
;                 const bf16x8 xs = __builtin_bit_cast(bf16x8, pw);
; #pragma unroll
;                 for (int db = 0; db < 2; ++db) O[qb][db] = MFMA32(Vf[db][s2], xs, O[qb][db]); }
;         }
; #pragma unroll
;         for (int s = 0; s < 6; ++s) Kf[s] = Kx[s];
;     }
; #pragma unroll
;     for (int qb = 0; qb < NQB; ++qb) { const float lt = sum_x32(lrun[qb]); const float inv = 1.0f / lt; float ss = 0.f;
; #pragma unroll
;         for (int db = 0; db < 2; ++db)
; #pragma unroll
;             for (int i = 0; i < 16; ++i) { O[qb][db][i] *= inv; ss += O[qb][db][i] * O[qb][db][i]; }
;         ss = sum_x32(ss);
;         if (hh == 0) red[h * 64 + qb * 32 + r] = ss; }
	v_cvt_pk_bf16_f32 v101, v97, v98
	v_cvt_pk_bf16_f32 v102, v68, v69
	v_pk_mul_f32 v[30:31], v[30:31], v[64:65] op_sel_hi:[1,0]
	v_pk_mul_f32 v[28:29], v[28:29], v[64:65] op_sel_hi:[1,0]
	v_pk_mul_f32 v[26:27], v[26:27], v[64:65] op_sel_hi:[1,0]
	v_pk_mul_f32 v[24:25], v[24:25], v[64:65] op_sel_hi:[1,0]
	v_pk_mul_f32 v[22:23], v[22:23], v[64:65] op_sel_hi:[1,0]
	v_pk_mul_f32 v[20:21], v[20:21], v[64:65] op_sel_hi:[1,0]
	v_pk_mul_f32 v[18:19], v[18:19], v[64:65] op_sel_hi:[1,0]
	v_pk_mul_f32 v[16:17], v[16:17], v[64:65] op_sel_hi:[1,0]
	v_cvt_pk_bf16_f32 v103, v70, v71
	v_mov_b32_e32 v66, v120
	s_nop 1
	v_permlane32_swap_b32_e32 v120, v66
	v_mfma_f32_32x32x16_bf16 v[16:31], v[92:95], v[100:103], v[16:31]
	v_mul_f32_e64 v14, v14, v64
	v_mul_f32_e64 v15, v15, v64
	v_mul_f32_e64 v12, v12, v64
	v_mul_f32_e64 v13, v13, v64
	v_mul_f32_e64 v10, v10, v64
	v_mul_f32_e64 v11, v11, v64
	v_pk_mul_f32 v[8:9], v[8:9], v[64:65] op_sel_hi:[1,0]
	v_pk_mul_f32 v[6:7], v[6:7], v[64:65] op_sel_hi:[1,0]
	v_pk_mul_f32 v[4:5], v[4:5], v[64:65] op_sel_hi:[1,0]
	v_pk_mul_f32 v[2:3], v[2:3], v[64:65] op_sel_hi:[1,0]
	v_pk_mul_f32 v[0:1], v[0:1], v[64:65] op_sel_hi:[1,0]
	v_add_f32_e32 v66, v120, v66
	v_div_scale_f32 v67, s[0:1], v66, v66, 1.0
	v_mfma_f32_32x32x16_bf16 v[0:15], v[88:91], v[100:103], v[0:15]
	v_cvt_pk_bf16_f32 v88, v72, v73
	v_cvt_pk_bf16_f32 v89, v74, v75
	v_cvt_pk_bf16_f32 v90, v76, v77
	v_cvt_pk_bf16_f32 v91, v78, v79
	s_nop 1
	v_mfma_f32_32x32x16_bf16 v[16:31], v[80:83], v[88:91], v[16:31]
	v_rcp_f32_e32 v80, v67
	s_nop 0
	v_fma_f32 v81, -v67, v80, 1.0
	v_fmac_f32_e32 v80, v81, v80
	v_div_scale_f32 v81, vcc, 1.0, v66, 1.0
	v_mul_f32_e32 v82, v81, v80
	v_fma_f32 v83, -v67, v82, v81
	v_fmac_f32_e32 v82, v83, v80
	v_fma_f32 v67, -v67, v82, v81
	v_div_fmas_f32 v67, v67, v80, v82
	v_div_fixup_f32 v80, v67, v66, 1.0
	v_pk_mul_f32 v[48:49], v[48:49], v[80:81] op_sel_hi:[1,0]
	v_pk_mul_f32 v[50:51], v[50:51], v[80:81] op_sel_hi:[1,0]
	v_mul_f32_e32 v66, v49, v49
	v_pk_fma_f32 v[66:67], v[48:49], v[48:49], v[66:67] op_sel_hi:[1,1,0]
	v_mul_f32_e32 v82, v51, v51
	v_pk_fma_f32 v[66:67], v[50:51], v[50:51], v[66:67]
	v_pk_mul_f32 v[52:53], v[52:53], v[80:81] op_sel_hi:[1,0]
	v_pk_add_f32 v[66:67], v[82:83], v[66:67] op_sel_hi:[0,1]
	v_pk_fma_f32 v[66:67], v[52:53], v[52:53], v[66:67]
	v_mul_f32_e32 v82, v53, v53
	v_pk_add_f32 v[66:67], v[82:83], v[66:67] op_sel_hi:[0,1]
	v_pk_mul_f32 v[54:55], v[54:55], v[80:81] op_sel_hi:[1,0]
	v_pk_mul_f32 v[56:57], v[56:57], v[80:81] op_sel_hi:[1,0]
	v_pk_fma_f32 v[66:67], v[54:55], v[54:55], v[66:67]
	v_mul_f32_e32 v82, v55, v55
	v_pk_add_f32 v[66:67], v[82:83], v[66:67] op_sel_hi:[0,1]
	v_pk_fma_f32 v[66:67], v[56:57], v[56:57], v[66:67]
	v_mul_f32_e32 v82, v57, v57
	v_pk_add_f32 v[66:67], v[82:83], v[66:67] op_sel_hi:[0,1]
	v_pk_mul_f32 v[58:59], v[58:59], v[80:81] op_sel_hi:[1,0]
	v_pk_mul_f32 v[60:61], v[60:61], v[80:81] op_sel_hi:[1,0]
	v_pk_fma_f32 v[66:67], v[58:59], v[58:59], v[66:67]
	v_mul_f32_e32 v82, v59, v59
	v_pk_add_f32 v[66:67], v[82:83], v[66:67] op_sel_hi:[0,1]
	v_pk_fma_f32 v[66:67], v[60:61], v[60:61], v[66:67]
	v_mul_f32_e32 v82, v61, v61
	v_pk_add_f32 v[66:67], v[82:83], v[66:67] op_sel_hi:[0,1]
	v_pk_mul_f32 v[62:63], v[62:63], v[80:81] op_sel_hi:[1,0]
	v_pk_mul_f32 v[32:33], v[32:33], v[80:81] op_sel_hi:[1,0]
	v_pk_fma_f32 v[66:67], v[62:63], v[62:63], v[66:67]
	v_mul_f32_e32 v82, v63, v63
	v_pk_add_f32 v[66:67], v[82:83], v[66:67] op_sel_hi:[0,1]
	v_pk_fma_f32 v[66:67], v[32:33], v[32:33], v[66:67]
	v_mul_f32_e32 v82, v33, v33
	v_pk_add_f32 v[66:67], v[82:83], v[66:67] op_sel_hi:[0,1]
	v_pk_mul_f32 v[34:35], v[34:35], v[80:81] op_sel_hi:[1,0]
	v_pk_mul_f32 v[36:37], v[36:37], v[80:81] op_sel_hi:[1,0]
	v_pk_fma_f32 v[66:67], v[34:35], v[34:35], v[66:67]
	v_mul_f32_e32 v82, v35, v35
	v_pk_add_f32 v[66:67], v[82:83], v[66:67] op_sel_hi:[0,1]
	v_pk_fma_f32 v[66:67], v[36:37], v[36:37], v[66:67]
	v_mul_f32_e32 v82, v37, v37
	v_pk_add_f32 v[66:67], v[82:83], v[66:67] op_sel_hi:[0,1]
	v_pk_mul_f32 v[38:39], v[38:39], v[80:81] op_sel_hi:[1,0]
	v_pk_mul_f32 v[40:41], v[40:41], v[80:81] op_sel_hi:[1,0]
	v_pk_fma_f32 v[66:67], v[38:39], v[38:39], v[66:67]
	v_mul_f32_e32 v82, v39, v39
	v_pk_add_f32 v[66:67], v[82:83], v[66:67] op_sel_hi:[0,1]
	v_pk_fma_f32 v[66:67], v[40:41], v[40:41], v[66:67]
	v_mul_f32_e32 v82, v41, v41
	v_pk_add_f32 v[82:83], v[82:83], v[66:67] op_sel_hi:[0,1]
	v_pk_mul_f32 v[66:67], v[42:43], v[80:81] op_sel_hi:[1,0]
	v_mfma_f32_32x32x16_bf16 v[0:15], v[84:87], v[88:91], v[0:15]
	v_fma_f32 v42, v66, v66, v82
	v_fma_f32 v43, v67, v67, v83
	v_mul_f32_e32 v82, v67, v67
	v_add_f32_e64 v42, v82, v42
	v_add_f32_e64 v43, v82, v43
	v_pk_mul_f32 v[44:45], v[44:45], v[80:81] op_sel_hi:[1,0]
	s_nop 0
	v_pk_fma_f32 v[42:43], v[44:45], v[44:45], v[42:43]
	v_mul_f32_e32 v82, v45, v45
	v_pk_add_f32 v[82:83], v[82:83], v[42:43] op_sel_hi:[0,1]
	v_pk_mul_f32 v[42:43], v[46:47], v[80:81] op_sel_hi:[1,0]
	s_nop 0
	v_pk_fma_f32 v[46:47], v[42:43], v[42:43], v[82:83]
	v_mul_f32_e32 v80, v43, v43
	v_pk_add_f32 v[46:47], v[80:81], v[46:47] op_sel_hi:[0,1]
	v_mov_b32_e32 v47, v46
	s_nop 1
	v_permlane32_swap_b32_e32 v46, v47
	s_and_saveexec_b64 s[4:5], s[42:43]
	v_add_f32_e32 v46, v46, v47
	v_add_u32_e32 v47, s29, v168
	ds_write_b32 v47, v46
	s_or_b64 exec, exec, s[4:5]
	v_add_f32_e32 v46, 0, v96
	v_add_f32_e32 v46, v65, v46
	v_add_f32_e32 v46, v97, v46
	v_add_f32_e32 v46, v98, v46
	v_add_f32_e32 v46, v68, v46
	v_add_f32_e32 v46, v69, v46
	v_add_f32_e32 v46, v70, v46
	v_add_f32_e32 v46, v71, v46
	v_add_f32_e32 v46, v72, v46
	v_add_f32_e32 v46, v73, v46
	v_add_f32_e32 v46, v74, v46
	v_add_f32_e32 v46, v75, v46
; __device__ __forceinline__ float sum_x32(float x) { float a, b; swap32(x, a, b); return a + b; }
; template <int NQB> ...
;     ...
;     for (int qb = 0; qb < NQB; ++qb) { const float lt = sum_x32(lrun[qb]); const float inv = 1.0f / lt; float ss = 0.f;
; #pragma unroll
;         for (int db = 0; db < 2; ++db)
; #pragma unroll
;             for (int i = 0; i < 16; ++i) { O[qb][db][i] *= inv; ss += O[qb][db][i] * O[qb][db][i]; }
;         ss = sum_x32(ss);
;         if (hh == 0) red[h * 64 + qb * 32 + r] = ss; }
;     __syncthreads();
	v_add_f32_e32 v46, v76, v46
	v_add_f32_e32 v46, v77, v46
	v_add_f32_e32 v46, v78, v46
	v_add_f32_e32 v46, v79, v46
	v_fmac_f32_e32 v46, v164, v64
	v_mov_b32_e32 v47, v46
	s_nop 1
	v_permlane32_swap_b32_e32 v46, v47
	v_add_f32_e32 v46, v46, v47
	v_div_scale_f32 v47, s[0:1], v46, v46, 1.0
	v_rcp_f32_e32 v64, v47
	s_nop 0
	v_fma_f32 v65, -v47, v64, 1.0
	v_fmac_f32_e32 v64, v65, v64
	v_div_scale_f32 v65, vcc, 1.0, v46, 1.0
	v_mul_f32_e32 v68, v65, v64
	v_fma_f32 v69, -v47, v68, v65
	v_fmac_f32_e32 v68, v69, v64
	v_fma_f32 v47, -v47, v68, v65
	v_div_fmas_f32 v47, v47, v64, v68
	v_div_fixup_f32 v46, v47, v46, 1.0
	v_pk_mul_f32 v[16:17], v[16:17], v[46:47] op_sel_hi:[1,0]
	v_pk_mul_f32 v[18:19], v[18:19], v[46:47] op_sel_hi:[1,0]
	v_mul_f32_e32 v64, v17, v17
	v_pk_fma_f32 v[64:65], v[16:17], v[16:17], v[64:65] op_sel_hi:[1,1,0]
	v_mul_f32_e32 v68, v19, v19
	v_pk_fma_f32 v[64:65], v[18:19], v[18:19], v[64:65]
	v_pk_mul_f32 v[20:21], v[20:21], v[46:47] op_sel_hi:[1,0]
	v_pk_add_f32 v[64:65], v[68:69], v[64:65] op_sel_hi:[0,1]
	v_pk_fma_f32 v[64:65], v[20:21], v[20:21], v[64:65]
	v_mul_f32_e32 v68, v21, v21
	v_pk_add_f32 v[64:65], v[68:69], v[64:65] op_sel_hi:[0,1]
	v_pk_mul_f32 v[22:23], v[22:23], v[46:47] op_sel_hi:[1,0]
	v_pk_mul_f32 v[24:25], v[24:25], v[46:47] op_sel_hi:[1,0]
	v_pk_fma_f32 v[64:65], v[22:23], v[22:23], v[64:65]
	v_mul_f32_e32 v68, v23, v23
	v_pk_add_f32 v[64:65], v[68:69], v[64:65] op_sel_hi:[0,1]
	v_pk_fma_f32 v[64:65], v[24:25], v[24:25], v[64:65]
	v_mul_f32_e32 v68, v25, v25
	v_pk_add_f32 v[64:65], v[68:69], v[64:65] op_sel_hi:[0,1]
	v_pk_mul_f32 v[26:27], v[26:27], v[46:47] op_sel_hi:[1,0]
	v_pk_mul_f32 v[28:29], v[28:29], v[46:47] op_sel_hi:[1,0]
	v_pk_fma_f32 v[64:65], v[26:27], v[26:27], v[64:65]
	v_mul_f32_e32 v68, v27, v27
	v_pk_add_f32 v[64:65], v[68:69], v[64:65] op_sel_hi:[0,1]
	v_pk_fma_f32 v[64:65], v[28:29], v[28:29], v[64:65]
	v_mul_f32_e32 v68, v29, v29
	v_pk_add_f32 v[64:65], v[68:69], v[64:65] op_sel_hi:[0,1]
	v_pk_mul_f32 v[30:31], v[30:31], v[46:47] op_sel_hi:[1,0]
	v_pk_mul_f32 v[0:1], v[0:1], v[46:47] op_sel_hi:[1,0]
	v_pk_fma_f32 v[64:65], v[30:31], v[30:31], v[64:65]
	v_mul_f32_e32 v68, v31, v31
	v_pk_add_f32 v[64:65], v[68:69], v[64:65] op_sel_hi:[0,1]
	v_pk_fma_f32 v[64:65], v[0:1], v[0:1], v[64:65]
	v_mul_f32_e32 v68, v1, v1
	v_pk_add_f32 v[64:65], v[68:69], v[64:65] op_sel_hi:[0,1]
	v_pk_mul_f32 v[2:3], v[2:3], v[46:47] op_sel_hi:[1,0]
	v_pk_mul_f32 v[4:5], v[4:5], v[46:47] op_sel_hi:[1,0]
	v_pk_fma_f32 v[64:65], v[2:3], v[2:3], v[64:65]
	v_mul_f32_e32 v68, v3, v3
	v_pk_add_f32 v[64:65], v[68:69], v[64:65] op_sel_hi:[0,1]
	v_pk_fma_f32 v[64:65], v[4:5], v[4:5], v[64:65]
	v_mul_f32_e32 v68, v5, v5
	v_pk_add_f32 v[64:65], v[68:69], v[64:65] op_sel_hi:[0,1]
	v_pk_mul_f32 v[6:7], v[6:7], v[46:47] op_sel_hi:[1,0]
	v_pk_mul_f32 v[8:9], v[8:9], v[46:47] op_sel_hi:[1,0]
	v_pk_fma_f32 v[64:65], v[6:7], v[6:7], v[64:65]
	v_mul_f32_e32 v68, v7, v7
	v_pk_add_f32 v[64:65], v[68:69], v[64:65] op_sel_hi:[0,1]
	v_pk_fma_f32 v[64:65], v[8:9], v[8:9], v[64:65]
	v_mul_f32_e32 v68, v9, v9
	v_pk_add_f32 v[64:65], v[68:69], v[64:65] op_sel_hi:[0,1]
	v_pk_mul_f32 v[10:11], v[10:11], v[46:47] op_sel_hi:[1,0]
	v_pk_mul_f32 v[12:13], v[12:13], v[46:47] op_sel_hi:[1,0]
	v_pk_fma_f32 v[64:65], v[10:11], v[10:11], v[64:65]
	v_mul_f32_e32 v68, v11, v11
	v_pk_add_f32 v[64:65], v[68:69], v[64:65] op_sel_hi:[0,1]
	v_pk_fma_f32 v[64:65], v[12:13], v[12:13], v[64:65]
	v_mul_f32_e32 v68, v13, v13
	v_pk_add_f32 v[64:65], v[68:69], v[64:65] op_sel_hi:[0,1]
	v_pk_mul_f32 v[14:15], v[14:15], v[46:47] op_sel_hi:[1,0]
	s_nop 0
	v_pk_fma_f32 v[46:47], v[14:15], v[14:15], v[64:65]
	v_mul_f32_e32 v64, v15, v15
	v_pk_add_f32 v[46:47], v[64:65], v[46:47] op_sel_hi:[0,1]
	v_mov_b32_e32 v47, v46
	s_nop 1
	v_permlane32_swap_b32_e32 v46, v47
	s_and_saveexec_b64 s[4:5], s[42:43]
	v_add_f32_e32 v46, v46, v47
	v_add_u32_e32 v47, s29, v168
	ds_write_b32 v47, v46 offset:128
	s_or_b64 exec, exec, s[4:5]
	s_waitcnt lgkmcnt(0)
	s_barrier
; __device__ __forceinline__ unsigned pkbf(float lo, float hi) { f2_t v = {lo, hi}; return __builtin_bit_cast(unsigned, __builtin_convertvector(v, bf2_t)); }
; template <int NQB> ...
;     ...
; #pragma unroll
;     for (int qb = 0; qb < NQB; ++qb) { float tot = 0.f;
; #pragma unroll
;         for (int w = 0; w < 8; ++w) tot += red[w * 64 + qb * 32 + r];
;         const float rs = rsqrtf(tot * (1.0f / 512.0f) + EPS);
;         bf16_t* op = A3 + (size_t)(qrow0 + 32 * qb + r) * 1024 + 512 + h * 64 + 4 * hh;
; #pragma unroll
;         for (int db = 0; db < 2; ++db)
; #pragma unroll
;             for (int g = 0; g < 4; ++g) { u32x2 w; w.x = pkbf(O[qb][db][4 * g] * rs, O[qb][db][4 * g + 1] * rs); w.y = pkbf(O[qb][db][4 * g + 2] * rs, O[qb][db][4 * g + 3] * rs);
;                 *(u32x2*)(op + 32 * db + 8 * g) = w; } }
;     __syncthreads();
	ds_read2_b32 v[46:47], v170 offset1:32
	ds_read2_b32 v[64:65], v170 offset0:64 offset1:96
	ds_read2_b32 v[68:69], v170 offset0:128 offset1:160
	ds_read2_b32 v[70:71], v170 offset0:192 offset1:224
	v_add_u32_e32 v78, 0x400, v170
	s_waitcnt lgkmcnt(3)
	v_mov_b32_e32 v80, v47
	v_mov_b32_e32 v81, v46
	v_pk_add_f32 v[46:47], v[80:81], 0 op_sel_hi:[1,0]
	s_waitcnt lgkmcnt(2)
	v_mov_b32_e32 v80, v65
	v_mov_b32_e32 v81, v64
	ds_read2_b32 v[72:73], v78 offset1:32
	ds_read2_b32 v[74:75], v78 offset0:64 offset1:96
	ds_read2_b32 v[76:77], v78 offset0:128 offset1:160
	ds_read2_b32 v[78:79], v78 offset0:192 offset1:224
	v_pk_add_f32 v[46:47], v[46:47], v[80:81]
	s_waitcnt lgkmcnt(5)
	v_mov_b32_e32 v64, v69
	v_mov_b32_e32 v65, v68
	v_pk_add_f32 v[46:47], v[46:47], v[64:65]
	s_waitcnt lgkmcnt(4)
	v_mov_b32_e32 v64, v71
	v_mov_b32_e32 v65, v70
	v_pk_add_f32 v[46:47], v[46:47], v[64:65]
	s_waitcnt lgkmcnt(3)
	v_mov_b32_e32 v64, v73
	v_mov_b32_e32 v65, v72
	v_pk_add_f32 v[46:47], v[46:47], v[64:65]
	s_waitcnt lgkmcnt(2)
	v_mov_b32_e32 v64, v75
	v_mov_b32_e32 v65, v74
	v_pk_add_f32 v[46:47], v[46:47], v[64:65]
	s_waitcnt lgkmcnt(1)
	v_mov_b32_e32 v64, v77
	v_mov_b32_e32 v65, v76
	v_pk_add_f32 v[46:47], v[46:47], v[64:65]
	s_waitcnt lgkmcnt(0)
	v_mov_b32_e32 v64, v79
	v_mov_b32_e32 v65, v78
	v_pk_add_f32 v[46:47], v[46:47], v[64:65]
	s_mov_b32 s0, 0x3b000000
	v_pk_fma_f32 v[46:47], v[46:47], s[0:1], v[134:135] op_sel_hi:[1,0,0]
	s_mov_b64 s[4:5], 0
	v_mul_f32_e32 v64, 0x4b800000, v47
	v_cmp_gt_f32_e32 vcc, s13, v47
	s_nop 1
	v_cndmask_b32_e32 v47, v47, v64, vcc
	v_rsq_f32_e32 v47, v47
	v_lshlrev_b64 v[64:65], 11, v[162:163]
	v_lshl_add_u64 v[64:65], v[140:141], 0, v[64:65]
	v_mul_f32_e32 v68, 0x45800000, v47
	v_cndmask_b32_e32 v68, v47, v68, vcc
	v_pk_mul_f32 v[32:33], v[32:33], v[68:69] op_sel_hi:[1,0]
	v_pk_mul_f32 v[34:35], v[34:35], v[68:69] op_sel_hi:[1,0]
	v_cvt_pk_bf16_f32 v32, v32, v33
	v_cvt_pk_bf16_f32 v33, v34, v35
	global_store_dwordx2 v[64:65], v[32:33], off offset:1088
	v_pk_mul_f32 v[32:33], v[36:37], v[68:69] op_sel_hi:[1,0]
	v_pk_mul_f32 v[34:35], v[38:39], v[68:69] op_sel_hi:[1,0]
	v_cvt_pk_bf16_f32 v32, v32, v33
	v_cvt_pk_bf16_f32 v33, v34, v35
	global_store_dwordx2 v[64:65], v[32:33], off offset:1104
	v_pk_mul_f32 v[32:33], v[40:41], v[68:69] op_sel_hi:[1,0]
	v_pk_mul_f32 v[34:35], v[66:67], v[68:69] op_sel_hi:[1,0]
	v_cvt_pk_bf16_f32 v32, v32, v33
	v_cvt_pk_bf16_f32 v33, v34, v35
	global_store_dwordx2 v[64:65], v[32:33], off offset:1120
	v_pk_mul_f32 v[32:33], v[44:45], v[68:69] op_sel_hi:[1,0]
	v_cmp_gt_f32_e32 vcc, s13, v46
	v_cvt_pk_bf16_f32 v32, v32, v33
	v_mul_f32_e32 v33, 0x4b800000, v46
	v_cndmask_b32_e32 v33, v46, v33, vcc
	v_rsq_f32_e32 v36, v33
	v_pk_mul_f32 v[34:35], v[42:43], v[68:69] op_sel_hi:[1,0]
	v_pk_mul_f32 v[48:49], v[48:49], v[68:69] op_sel_hi:[1,0]
	v_cvt_pk_bf16_f32 v33, v34, v35
	global_store_dwordx2 v[64:65], v[32:33], off offset:1136
	v_mul_f32_e32 v32, 0x45800000, v36
	v_cndmask_b32_e32 v32, v36, v32, vcc
	v_pk_mul_f32 v[50:51], v[50:51], v[68:69] op_sel_hi:[1,0]
	v_lshlrev_b64 v[34:35], 11, v[160:161]
	v_pk_mul_f32 v[16:17], v[16:17], v[32:33] op_sel_hi:[1,0]
	v_pk_mul_f32 v[18:19], v[18:19], v[32:33] op_sel_hi:[1,0]
	v_pk_mul_f32 v[0:1], v[0:1], v[32:33] op_sel_hi:[1,0]
	v_pk_mul_f32 v[2:3], v[2:3], v[32:33] op_sel_hi:[1,0]
	v_cvt_pk_bf16_f32 v48, v48, v49
	v_cvt_pk_bf16_f32 v49, v50, v51
	v_lshl_add_u64 v[34:35], v[140:141], 0, v[34:35]
	v_cvt_pk_bf16_f32 v16, v16, v17
	v_cvt_pk_bf16_f32 v17, v18, v19
	v_cvt_pk_bf16_f32 v0, v0, v1
	v_cvt_pk_bf16_f32 v1, v2, v3
	global_store_dwordx2 v[64:65], v[48:49], off offset:1024
	v_pk_mul_f32 v[48:49], v[52:53], v[68:69] op_sel_hi:[1,0]
	v_pk_mul_f32 v[50:51], v[54:55], v[68:69] op_sel_hi:[1,0]
	global_store_dwordx2 v[34:35], v[16:17], off offset:1024
	v_pk_mul_f32 v[16:17], v[20:21], v[32:33] op_sel_hi:[1,0]
	v_pk_mul_f32 v[18:19], v[22:23], v[32:33] op_sel_hi:[1,0]
	global_store_dwordx2 v[34:35], v[0:1], off offset:1088
	v_pk_mul_f32 v[0:1], v[4:5], v[32:33] op_sel_hi:[1,0]
	v_pk_mul_f32 v[2:3], v[6:7], v[32:33] op_sel_hi:[1,0]
	v_cvt_pk_bf16_f32 v48, v48, v49
	v_cvt_pk_bf16_f32 v49, v50, v51
	v_cvt_pk_bf16_f32 v16, v16, v17
	v_cvt_pk_bf16_f32 v17, v18, v19
	v_cvt_pk_bf16_f32 v0, v0, v1
	v_cvt_pk_bf16_f32 v1, v2, v3
	global_store_dwordx2 v[64:65], v[48:49], off offset:1040
	v_pk_mul_f32 v[48:49], v[56:57], v[68:69] op_sel_hi:[1,0]
	v_pk_mul_f32 v[50:51], v[58:59], v[68:69] op_sel_hi:[1,0]
	global_store_dwordx2 v[34:35], v[16:17], off offset:1040
	v_pk_mul_f32 v[16:17], v[24:25], v[32:33] op_sel_hi:[1,0]
	v_pk_mul_f32 v[18:19], v[26:27], v[32:33] op_sel_hi:[1,0]
	global_store_dwordx2 v[34:35], v[0:1], off offset:1104
	v_pk_mul_f32 v[0:1], v[8:9], v[32:33] op_sel_hi:[1,0]
	v_pk_mul_f32 v[2:3], v[10:11], v[32:33] op_sel_hi:[1,0]
	v_cvt_pk_bf16_f32 v48, v48, v49
	v_cvt_pk_bf16_f32 v49, v50, v51
	v_cvt_pk_bf16_f32 v16, v16, v17
	v_cvt_pk_bf16_f32 v17, v18, v19
	v_cvt_pk_bf16_f32 v0, v0, v1
	v_cvt_pk_bf16_f32 v1, v2, v3
	global_store_dwordx2 v[64:65], v[48:49], off offset:1056
	v_pk_mul_f32 v[48:49], v[60:61], v[68:69] op_sel_hi:[1,0]
	v_pk_mul_f32 v[50:51], v[62:63], v[68:69] op_sel_hi:[1,0]
	global_store_dwordx2 v[34:35], v[16:17], off offset:1056
	v_pk_mul_f32 v[16:17], v[28:29], v[32:33] op_sel_hi:[1,0]
	v_pk_mul_f32 v[18:19], v[30:31], v[32:33] op_sel_hi:[1,0]
	global_store_dwordx2 v[34:35], v[0:1], off offset:1120
	v_pk_mul_f32 v[0:1], v[12:13], v[32:33] op_sel_hi:[1,0]
	v_pk_mul_f32 v[2:3], v[14:15], v[32:33] op_sel_hi:[1,0]
	v_cvt_pk_bf16_f32 v48, v48, v49
	v_cvt_pk_bf16_f32 v49, v50, v51
	v_cvt_pk_bf16_f32 v16, v16, v17
	v_cvt_pk_bf16_f32 v17, v18, v19
	v_cvt_pk_bf16_f32 v0, v0, v1
	v_cvt_pk_bf16_f32 v1, v2, v3
	global_store_dwordx2 v[64:65], v[48:49], off offset:1072
	global_store_dwordx2 v[34:35], v[16:17], off offset:1072
	global_store_dwordx2 v[34:35], v[0:1], off offset:1136
	s_barrier
